# v39 + nt hint on the norm1 phase's H (bf16 activations) stores
# baseline (speedup 1.0000x reference)
; __global__ void __launch_bounds__(NWAVES * 64, 2) fwd_kernel(Args args_unused) {
;     ...
;         { const int nrow = grouped ? (4 * SEQ + 4 * CTXL) : MT;
;           for (int r = gw; r < nrow; r += NGW) { const int mrow = (!grouped || r < 4 * SEQ) ? r : ML + (r - 4 * SEQ); P1_ROW(mrow); } }
.LBB0_173:
	v_lshl_add_u64 v[30:31], s[20:21], 0, v[4:5]
	global_load_dwordx4 v[14:17], v[30:31], off nt
	global_load_dwordx4 v[18:21], v[30:31], off offset:1024 nt
	global_load_dwordx4 v[22:25], v[30:31], off offset:3072 nt
	global_load_dwordx4 v[26:29], v[30:31], off offset:2048 nt
	s_min_i32 s8, s16, 0x8000
	s_ashr_i32 s8, s8, 12
	s_mul_hi_i32 s21, s8, 0x6000
	s_mulk_i32 s8, 0x6000
	s_add_u32 s20, s12, s8
	s_addc_u32 s21, s13, s21
	v_lshl_add_u64 v[54:55], s[20:21], 0, v[4:5]
	v_add_co_u32_e32 v30, vcc, s3, v54
	v_lshl_add_u64 v[56:57], v[54:55], 0, s[14:15]
	s_nop 0
	v_addc_co_u32_e32 v31, vcc, 0, v55, vcc
	global_load_dwordx4 v[30:33], v[30:31], off nt
	s_nop 0
	global_load_dwordx4 v[34:37], v[56:57], off offset:1024 nt
	global_load_dwordx4 v[38:41], v[2:3], off offset:1024 nt
	global_load_dwordx4 v[42:45], v[2:3], off nt
	global_load_dwordx4 v[46:49], v[54:55], off offset:1024 nt
	global_load_dwordx4 v[50:53], v[54:55], off nt
	s_lshl_b64 s[16:17], s[16:17], 11
	s_add_i32 s23, s23, s24
	s_cmp_ge_i32 s23, s0
	s_waitcnt vmcnt(9)
	v_pk_mul_f32 v[58:59], v[16:17], v[16:17]
	v_pk_mul_f32 v[60:61], v[14:15], v[14:15]
	s_waitcnt vmcnt(8)
	v_pk_mul_f32 v[62:63], v[20:21], v[20:21]
	v_pk_mul_f32 v[64:65], v[18:19], v[18:19]
	v_pk_mov_b32 v[70:71], v[60:61], v[58:59] op_sel:[1,0]
	v_mov_b32_e32 v61, v59
	v_pk_mov_b32 v[58:59], v[64:65], v[62:63] op_sel:[1,0]
	v_mov_b32_e32 v65, v63
	s_waitcnt vmcnt(7)
	v_mul_f32_e32 v69, v23, v23
	s_waitcnt vmcnt(6)
	v_mul_f32_e32 v66, v27, v27
	v_mul_f32_e32 v68, v29, v29
	v_pk_add_f32 v[60:61], v[70:71], v[60:61]
	v_pk_add_f32 v[58:59], v[58:59], v[64:65]
	v_mul_f32_e32 v13, v22, v22
	v_mul_f32_e32 v72, v24, v24
	v_mul_f32_e32 v73, v25, v25
	v_pk_fma_f32 v[62:63], v[26:27], v[26:27], v[66:67] op_sel_hi:[1,1,0]
	v_pk_fma_f32 v[66:67], v[28:29], v[28:29], v[68:69] op_sel_hi:[1,1,0]
	v_pk_add_f32 v[60:61], v[60:61], v[60:61] op_sel:[0,1] op_sel_hi:[1,0]
	v_pk_add_f32 v[58:59], v[58:59], v[58:59] op_sel:[0,1] op_sel_hi:[1,0]
	v_mov_b32_e32 v63, v72
	v_mov_b32_e32 v67, v73
	v_mov_b32_e32 v61, v13
	v_mov_b32_e32 v59, v69
	v_pk_add_f32 v[62:63], v[62:63], v[66:67]
	v_pk_add_f32 v[58:59], v[60:61], v[58:59]
	s_waitcnt vmcnt(5)
	v_pk_add_f32 v[32:33], v[32:33], 1.0 op_sel_hi:[1,0]
	v_pk_add_f32 v[58:59], v[58:59], v[62:63]
	v_pk_add_f32 v[30:31], v[30:31], 1.0 op_sel_hi:[1,0]
	v_add_f32_e32 v13, v58, v59
	ds_bpermute_b32 v58, v6, v13
	s_waitcnt vmcnt(4)
	v_pk_add_f32 v[36:37], v[36:37], 1.0 op_sel_hi:[1,0]
	v_pk_add_f32 v[34:35], v[34:35], 1.0 op_sel_hi:[1,0]
	s_waitcnt lgkmcnt(0)
	v_add_f32_e32 v13, v13, v58
	ds_bpermute_b32 v58, v7, v13
	s_waitcnt lgkmcnt(0)
	v_add_f32_e32 v13, v13, v58
	ds_bpermute_b32 v58, v8, v13
	s_waitcnt lgkmcnt(0)
	v_add_f32_e32 v13, v13, v58
	ds_bpermute_b32 v58, v9, v13
	s_waitcnt lgkmcnt(0)
	v_add_f32_e32 v13, v13, v58
	ds_bpermute_b32 v58, v10, v13
	s_waitcnt lgkmcnt(0)
	v_add_f32_e32 v13, v13, v58
	ds_bpermute_b32 v60, v11, v13
	v_lshl_add_u64 v[58:59], v[0:1], 0, s[16:17]
	s_waitcnt lgkmcnt(0)
	v_add_f32_e32 v13, v13, v60
	v_fmamk_f32 v13, v13, 0x3a800000, v12
	v_mul_f32_e32 v60, 0x4b800000, v13
	v_cmp_gt_f32_e32 vcc, s1, v13
	s_nop 1
	v_cndmask_b32_e32 v13, v13, v60, vcc
	v_rsq_f32_e32 v13, v13
	s_nop 0
	v_mul_f32_e32 v60, 0x45800000, v13
	v_cndmask_b32_e32 v60, v13, v60, vcc
	v_pk_mul_f32 v[16:17], v[60:61], v[16:17] op_sel_hi:[0,1]
	v_pk_mul_f32 v[14:15], v[60:61], v[14:15] op_sel_hi:[0,1]
	v_pk_mul_f32 v[20:21], v[60:61], v[20:21] op_sel_hi:[0,1]
	v_pk_mul_f32 v[18:19], v[60:61], v[18:19] op_sel_hi:[0,1]
	s_waitcnt vmcnt(2)
	v_pk_mul_f32 v[14:15], v[42:43], v[14:15]
	v_pk_mul_f32 v[16:17], v[44:45], v[16:17]
	v_pk_mul_f32 v[18:19], v[38:39], v[18:19]
	v_pk_mul_f32 v[20:21], v[40:41], v[20:21]
	s_waitcnt vmcnt(0)
	v_pk_fma_f32 v[16:17], v[32:33], v[16:17], v[52:53]
	v_pk_fma_f32 v[14:15], v[30:31], v[14:15], v[50:51]
	v_pk_fma_f32 v[20:21], v[36:37], v[20:21], v[48:49]
	v_pk_fma_f32 v[18:19], v[34:35], v[18:19], v[46:47]
	v_cvt_pk_bf16_f32 v14, v14, v15
	v_cvt_pk_bf16_f32 v15, v16, v17
	v_cvt_pk_bf16_f32 v16, v18, v19
	v_cvt_pk_bf16_f32 v17, v20, v21
	global_store_dwordx2 v[58:59], v[14:15], off nt
	global_store_dwordx2 v[58:59], v[16:17], off offset:512 nt
	global_load_dwordx4 v[14:17], v[56:57], off offset:2048 nt
	s_nop 0
	global_load_dwordx4 v[18:21], v[2:3], off offset:2048 nt
	global_load_dwordx4 v[30:33], v[56:57], off offset:3072 nt
	global_load_dwordx4 v[34:37], v[2:3], off offset:3072 nt
	global_load_dwordx4 v[38:41], v[54:55], off offset:2048 nt
	global_load_dwordx4 v[42:45], v[54:55], off offset:3072 nt
	v_pk_mul_f32 v[28:29], v[60:61], v[28:29] op_sel_hi:[0,1]
	v_pk_mul_f32 v[26:27], v[60:61], v[26:27] op_sel_hi:[0,1]
	v_pk_mul_f32 v[24:25], v[60:61], v[24:25] op_sel_hi:[0,1]
	v_pk_mul_f32 v[22:23], v[60:61], v[22:23] op_sel_hi:[0,1]
	s_waitcnt vmcnt(5)
	v_pk_add_f32 v[16:17], v[16:17], 1.0 op_sel_hi:[1,0]
	v_pk_add_f32 v[14:15], v[14:15], 1.0 op_sel_hi:[1,0]
	s_waitcnt vmcnt(4)
	v_pk_mul_f32 v[18:19], v[18:19], v[26:27]
	v_pk_mul_f32 v[20:21], v[20:21], v[28:29]
	s_waitcnt vmcnt(3)
	v_pk_add_f32 v[26:27], v[32:33], 1.0 op_sel_hi:[1,0]
	v_pk_add_f32 v[28:29], v[30:31], 1.0 op_sel_hi:[1,0]
	s_waitcnt vmcnt(2)
	v_pk_mul_f32 v[22:23], v[34:35], v[22:23]
	v_pk_mul_f32 v[24:25], v[36:37], v[24:25]
	s_waitcnt vmcnt(1)
	v_pk_fma_f32 v[16:17], v[16:17], v[20:21], v[40:41]
	v_pk_fma_f32 v[14:15], v[14:15], v[18:19], v[38:39]
	s_waitcnt vmcnt(0)
	v_pk_fma_f32 v[18:19], v[26:27], v[24:25], v[44:45]
	v_pk_fma_f32 v[20:21], v[28:29], v[22:23], v[42:43]
	v_cvt_pk_bf16_f32 v14, v14, v15
	v_cvt_pk_bf16_f32 v15, v16, v17
	v_cvt_pk_bf16_f32 v16, v20, v21
	v_cvt_pk_bf16_f32 v17, v18, v19
	global_store_dwordx2 v[58:59], v[14:15], off offset:1024 nt
	global_store_dwordx2 v[58:59], v[16:17], off offset:1536 nt
	s_cbranch_scc1 .LBB0_178
